# first norm phase: the 1024 context rows are normalised by workgroups 128..255 (fold workgroups) instead of 0..127 (the GEMV workgroups, which also carry the double transpose items)
# baseline (speedup 1.0000x reference)
; __global__ void __launch_bounds__(512, 2) mk_fwd(Args A) {
;     ...
;         for (int r = pgw; r < MCTX; r += NGW)
;             rownorm1<true>(A.in[I_CTX] + (size_t)r * DM, nullptr, A.in[I_N1G], mod + NB * MODLD + 0 * DM, mod + NB * MODLD + 1 * DM, XN + (size_t)(MLAT + r) * DM, nullptr, plane);
.LBB0_257:
	s_xor_b32 s6, s6, 0x400
	s_cmpk_gt_i32 s6, 0x3ff
	s_cbranch_scc0 .LBB0_260
	s_branch .LBB0_262

; template <bool MOD>
; __device__ __forceinline__ void rownorm1(const float* xrow, const bf16_t* part, const float* g, const float* shift, const float* scale, bf16_t* obf, float* of32, int lane) {
;     f32x4 v[4]; float ss = 0.f;
; #pragma unroll
;     for (int j = 0; j < 4; ++j) { v[j] = ((const f32x4*)xrow)[lane + 64 * j]; if (part) {
;             for (int ks = 0; ks < 11; ++ks) { const u32x2 w = ((const u32x2*)(part + (size_t)ks * MCTX * DM))[lane + 64 * j];
;                 v[j][0] += __uint_as_float(w.x << 16); v[j][1] += __uint_as_float(w.x & 0xffff0000u); v[j][2] += __uint_as_float(w.y << 16); v[j][3] += __uint_as_float(w.y & 0xffff0000u); } }
;         ss += (v[j][0] * v[j][0] + v[j][1] * v[j][1]) + (v[j][2] * v[j][2] + v[j][3] * v[j][3]); }
;     const float rstd = 1.0f / sqrtf(wave_sum(ss) * (1.0f / DM) + RMS_EPS);
; __global__ void __launch_bounds__(512, 2) mk_fwd(Args A) {
;     ...
;         for (int r = pgw; r < MCTX; r += NGW)
;             rownorm1<true>(A.in[I_CTX] + (size_t)r * DM, nullptr, A.in[I_N1G], mod + NB * MODLD + 0 * DM, mod + NB * MODLD + 1 * DM, XN + (size_t)(MLAT + r) * DM, nullptr, plane);
.LBB0_259:
	s_ashr_i32 s11, s10, 31
	s_lshr_b32 s0, s11, 20
	s_add_i32 s0, s10, s0
	s_ashr_i32 s0, s0, 12
	s_mulk_i32 s0, 0x2400
	s_ashr_i32 s1, s0, 31
	s_lshl_b64 s[0:1], s[0:1], 2
	s_add_u32 s2, s64, s0
	s_addc_u32 s3, s65, s1
	s_lshl_b64 s[0:1], s[10:11], 12
	s_add_u32 s0, s76, s0
	s_addc_u32 s1, s77, s1
	global_load_dwordx4 v[14:17], v32, s[0:1]
	global_load_dwordx4 v[8:11], v32, s[0:1] offset:1024
	global_load_dwordx4 v[0:3], v32, s[0:1] offset:3072
	global_load_dwordx4 v[4:7], v32, s[0:1] offset:2048
	v_mbcnt_lo_u32_b32 v13, -1, 0
	v_mbcnt_hi_u32_b32 v13, -1, v13
	v_and_b32_e32 v22, 64, v13
	s_add_u32 s8, s2, 0x1000
	v_xor_b32_e32 v23, 1, v13
	v_add_u32_e32 v33, 64, v22
	s_addc_u32 s9, s3, 0
	v_cmp_lt_i32_e32 vcc, v23, v33
	global_load_dwordx4 v[18:21], v32, s[8:9]
	s_mov_b32 s7, 0xf800000
	v_cndmask_b32_e32 v22, v13, v23, vcc
	v_lshlrev_b32_e32 v43, 2, v22
	global_load_dwordx4 v[22:25], v32, s[88:89]
	global_load_dwordx4 v[26:29], v32, s[2:3]
	s_lshl_b64 s[0:1], s[10:11], 11
	s_add_u32 s10, s18, s0
	s_addc_u32 s11, s19, s1
	s_waitcnt vmcnt(6)
	v_pk_mul_f32 v[30:31], v[16:17], v[16:17]
	v_pk_mul_f32 v[34:35], v[14:15], v[14:15]
	s_waitcnt vmcnt(5)
	v_pk_mul_f32 v[36:37], v[10:11], v[10:11]
	v_pk_mul_f32 v[38:39], v[8:9], v[8:9]
	v_pk_mov_b32 v[44:45], v[34:35], v[30:31] op_sel:[1,0]
	v_mov_b32_e32 v35, v31
	v_pk_mov_b32 v[30:31], v[38:39], v[36:37] op_sel:[1,0]
	v_mov_b32_e32 v39, v37
	s_waitcnt vmcnt(3)
	v_mul_f32_e32 v40, v5, v5
	v_mul_f32_e32 v42, v7, v7
	v_pk_add_f32 v[34:35], v[44:45], v[34:35]
	v_pk_add_f32 v[30:31], v[30:31], v[38:39]
	v_mul_f32_e32 v46, v0, v0
	v_mul_f32_e32 v47, v1, v1
	v_mul_f32_e32 v48, v2, v2
	v_mul_f32_e32 v49, v3, v3
	v_pk_fma_f32 v[36:37], v[4:5], v[4:5], v[40:41] op_sel_hi:[1,1,0]
	v_pk_fma_f32 v[40:41], v[6:7], v[6:7], v[42:43] op_sel_hi:[1,1,0]
	v_pk_add_f32 v[34:35], v[34:35], v[34:35] op_sel:[0,1] op_sel_hi:[1,0]
	v_pk_add_f32 v[30:31], v[30:31], v[30:31] op_sel:[0,1] op_sel_hi:[1,0]
	v_mov_b32_e32 v37, v48
	v_mov_b32_e32 v41, v49
	v_mov_b32_e32 v35, v46
	v_mov_b32_e32 v31, v47
	v_pk_add_f32 v[36:37], v[36:37], v[40:41]
	v_pk_add_f32 v[30:31], v[34:35], v[30:31]
	v_xor_b32_e32 v34, 2, v13
	v_pk_add_f32 v[30:31], v[30:31], v[36:37]
	v_cmp_lt_i32_e32 vcc, v34, v33
	v_add_f32_e32 v30, v30, v31
	ds_bpermute_b32 v31, v43, v30
	v_cndmask_b32_e32 v34, v13, v34, vcc
	v_lshlrev_b32_e32 v34, 2, v34
	s_waitcnt vmcnt(2)
	v_pk_add_f32 v[18:19], v[18:19], 1.0 op_sel_hi:[1,0]
	v_pk_add_f32 v[20:21], v[20:21], 1.0 op_sel_hi:[1,0]
	s_waitcnt lgkmcnt(0)
	v_add_f32_e32 v30, v30, v31
	ds_bpermute_b32 v31, v34, v30
	v_xor_b32_e32 v34, 4, v13
	v_cmp_lt_i32_e32 vcc, v34, v33
	s_waitcnt lgkmcnt(0)
	v_add_f32_e32 v30, v30, v31
	v_cndmask_b32_e32 v34, v13, v34, vcc
	v_lshlrev_b32_e32 v34, 2, v34
	ds_bpermute_b32 v31, v34, v30
	v_xor_b32_e32 v34, 8, v13
	v_cmp_lt_i32_e32 vcc, v34, v33
	s_waitcnt lgkmcnt(0)
	v_add_f32_e32 v30, v30, v31
	v_cndmask_b32_e32 v34, v13, v34, vcc
	v_lshlrev_b32_e32 v34, 2, v34
	ds_bpermute_b32 v31, v34, v30
	v_xor_b32_e32 v34, 16, v13
	v_cmp_lt_i32_e32 vcc, v34, v33
	s_waitcnt lgkmcnt(0)
	v_add_f32_e32 v30, v30, v31
	v_cndmask_b32_e32 v34, v13, v34, vcc
	v_lshlrev_b32_e32 v34, 2, v34
	ds_bpermute_b32 v31, v34, v30
	v_xor_b32_e32 v34, 32, v13
	v_cmp_lt_i32_e32 vcc, v34, v33
	v_mov_b32_e32 v33, 0x260
	s_waitcnt lgkmcnt(0)
	v_add_f32_e32 v30, v30, v31
	v_cndmask_b32_e32 v13, v13, v34, vcc
	v_lshlrev_b32_e32 v13, 2, v13
	ds_bpermute_b32 v13, v13, v30
	v_mov_b32_e32 v31, 0x358637bd
	s_waitcnt lgkmcnt(0)
; __device__ __forceinline__ unsigned cvt_pk_bf16(float lo, float hi) { unsigned r; asm volatile("v_cvt_pk_bf16_f32 %0, %1, %2" : "=v"(r) : "v"(lo), "v"(hi)); return r; }
; template <bool MOD>
; __device__ __forceinline__ void rownorm1(const float* xrow, const bf16_t* part, const float* g, const float* shift, const float* scale, bf16_t* obf, float* of32, int lane) {
;     ...
;     const float rstd = 1.0f / sqrtf(wave_sum(ss) * (1.0f / DM) + RMS_EPS);
; #pragma unroll
;     for (int j = 0; j < 4; ++j) {
;         const f32x4 gv = ((const f32x4*)g)[lane + 64 * j];
;         f32x4 y = v[j] * rstd * gv;
;         if (MOD) { const f32x4 sh = ((const f32x4*)shift)[lane + 64 * j], sc = ((const f32x4*)scale)[lane + 64 * j]; y = y * (sc + 1.0f) + sh;
;             u32x2 w; w.x = cvt_pk_bf16(y[0], y[1]); w.y = cvt_pk_bf16(y[2], y[3]); ((u32x2*)obf)[lane + 64 * j] = w; }
;         else ((f32x4*)of32)[lane + 64 * j] = y;
;     }
; __global__ void __launch_bounds__(512, 2) mk_fwd(Args A) {
;     ...
;         for (int r = pgw; r < MCTX; r += NGW)
;             rownorm1<true>(A.in[I_CTX] + (size_t)r * DM, nullptr, A.in[I_N1G], mod + NB * MODLD + 0 * DM, mod + NB * MODLD + 1 * DM, XN + (size_t)(MLAT + r) * DM, nullptr, plane);
	v_add_f32_e32 v13, v30, v13
	v_fmac_f32_e32 v31, 0x3a800000, v13
	v_mul_f32_e32 v13, 0x4f800000, v31
	v_cmp_gt_f32_e32 vcc, s7, v31
	s_nop 1
	v_cndmask_b32_e32 v13, v31, v13, vcc
	v_sqrt_f32_e32 v30, v13
	s_nop 0
	v_add_u32_e32 v31, -1, v30
	v_add_u32_e32 v34, 1, v30
	v_fma_f32 v35, -v31, v30, v13
	v_fma_f32 v36, -v34, v30, v13
	v_cmp_ge_f32_e64 s[0:1], 0, v35
	s_nop 1
	v_cndmask_b32_e64 v30, v30, v31, s[0:1]
	v_cmp_lt_f32_e64 s[0:1], 0, v36
	s_nop 1
	v_cndmask_b32_e64 v30, v30, v34, s[0:1]
	v_mul_f32_e32 v31, 0x37800000, v30
	v_cndmask_b32_e32 v30, v30, v31, vcc
	v_cmp_class_f32_e32 vcc, v13, v33
	s_nop 1
	v_cndmask_b32_e32 v13, v30, v13, vcc
	v_div_scale_f32 v30, s[0:1], v13, v13, 1.0
	v_rcp_f32_e32 v31, v30
	v_div_scale_f32 v33, vcc, 1.0, v13, 1.0
	v_fma_f32 v34, -v30, v31, 1.0
	v_fmac_f32_e32 v31, v34, v31
	v_mul_f32_e32 v34, v33, v31
	v_fma_f32 v35, -v30, v34, v33
	v_fmac_f32_e32 v34, v35, v31
	v_fma_f32 v30, -v30, v34, v33
	v_div_fmas_f32 v30, v30, v31, v34
	v_div_fixup_f32 v30, v30, v13, 1.0
	v_pk_mul_f32 v[14:15], v[14:15], v[30:31] op_sel_hi:[1,0]
	v_pk_mul_f32 v[16:17], v[16:17], v[30:31] op_sel_hi:[1,0]
	s_waitcnt vmcnt(1)
	v_pk_mul_f32 v[14:15], v[22:23], v[14:15]
	v_pk_mul_f32 v[16:17], v[24:25], v[16:17]
	s_waitcnt vmcnt(0)
	v_pk_fma_f32 v[14:15], v[18:19], v[14:15], v[26:27]
	v_pk_fma_f32 v[16:17], v[20:21], v[16:17], v[28:29]
	v_cvt_pk_bf16_f32 v14, v14, v15
	v_or_b32_e32 v13, 0x400, v32
	v_cvt_pk_bf16_f32 v15, v16, v17
	global_store_dwordx2 v12, v[14:15], s[10:11]
	global_load_dwordx4 v[14:17], v32, s[88:89] offset:1024
	s_nop 0
	global_load_dwordx4 v[18:21], v13, s[8:9]
	global_load_dwordx4 v[22:25], v32, s[2:3] offset:1024
	v_pk_mul_f32 v[10:11], v[10:11], v[30:31] op_sel_hi:[1,0]
	v_pk_mul_f32 v[8:9], v[8:9], v[30:31] op_sel_hi:[1,0]
	v_or_b32_e32 v13, 0x800, v32
	v_pk_mul_f32 v[6:7], v[6:7], v[30:31] op_sel_hi:[1,0]
	v_pk_mul_f32 v[4:5], v[4:5], v[30:31] op_sel_hi:[1,0]
	v_pk_mul_f32 v[2:3], v[2:3], v[30:31] op_sel_hi:[1,0]
	v_pk_mul_f32 v[0:1], v[0:1], v[30:31] op_sel_hi:[1,0]
	s_waitcnt vmcnt(2)
	v_pk_mul_f32 v[8:9], v[14:15], v[8:9]
	v_pk_mul_f32 v[10:11], v[16:17], v[10:11]
	s_waitcnt vmcnt(1)
	v_pk_add_f32 v[16:17], v[18:19], 1.0 op_sel_hi:[1,0]
	v_pk_add_f32 v[14:15], v[20:21], 1.0 op_sel_hi:[1,0]
	s_waitcnt vmcnt(0)
	v_pk_fma_f32 v[8:9], v[16:17], v[8:9], v[22:23]
	v_pk_fma_f32 v[10:11], v[14:15], v[10:11], v[24:25]
	v_cvt_pk_bf16_f32 v8, v8, v9
	s_nop 0
	v_cvt_pk_bf16_f32 v9, v10, v11
	global_store_dwordx2 v12, v[8:9], s[10:11] offset:512
	global_load_dwordx4 v[8:11], v32, s[88:89] offset:2048
	s_nop 0
	global_load_dwordx4 v[14:17], v13, s[8:9]
	global_load_dwordx4 v[18:21], v32, s[2:3] offset:2048
	s_waitcnt vmcnt(2)
	v_pk_mul_f32 v[4:5], v[4:5], v[8:9]
	v_pk_mul_f32 v[6:7], v[6:7], v[10:11]
	s_waitcnt vmcnt(1)
	v_pk_add_f32 v[10:11], v[14:15], 1.0 op_sel_hi:[1,0]
	v_pk_add_f32 v[8:9], v[16:17], 1.0 op_sel_hi:[1,0]
	s_waitcnt vmcnt(0)
	v_pk_fma_f32 v[4:5], v[4:5], v[10:11], v[18:19]
	v_pk_fma_f32 v[6:7], v[6:7], v[8:9], v[20:21]
	v_cvt_pk_bf16_f32 v4, v4, v5
	v_or_b32_e32 v8, 0xc00, v32
	v_cvt_pk_bf16_f32 v5, v6, v7
	global_store_dwordx2 v12, v[4:5], s[10:11] offset:1024
	global_load_dwordx4 v[4:7], v32, s[88:89] offset:3072
	s_nop 0
	global_load_dwordx4 v[8:11], v8, s[8:9]
	s_nop 0
	global_load_dwordx4 v[14:17], v32, s[2:3] offset:3072
	s_waitcnt vmcnt(2)
	v_pk_mul_f32 v[0:1], v[0:1], v[4:5]
	v_pk_mul_f32 v[2:3], v[2:3], v[6:7]
	s_waitcnt vmcnt(1)
	v_pk_add_f32 v[6:7], v[8:9], 1.0 op_sel_hi:[1,0]
	v_pk_add_f32 v[4:5], v[10:11], 1.0 op_sel_hi:[1,0]
	s_waitcnt vmcnt(0)
	v_pk_fma_f32 v[0:1], v[0:1], v[6:7], v[14:15]
	v_pk_fma_f32 v[2:3], v[2:3], v[4:5], v[16:17]
	v_cvt_pk_bf16_f32 v0, v0, v1
	s_nop 0
	v_cvt_pk_bf16_f32 v1, v2, v3
	global_store_dwordx2 v12, v[0:1], s[10:11] offset:1536
	s_xor_b32 s6, s6, 0x400
	s_cmpk_gt_i32 s6, 0x3ff
	s_cbranch_scc1 .LBB0_262
